# rstd table build restricted to the workgroup's own 256-row panel (tile map gives one row panel per workgroup per phase) at P4/P6/P10/P17; stacked on accumulator-zeroing peel and SWA prologue fix
# speedup vs baseline: 1.0100x; 1.0003x over previous
.LBB0_462:
	s_ashr_i32 s2, s2, 3
	s_add_i32 s2, s9, s2
	s_ashr_i32 s4, s2, 31
	s_lshr_b32 s4, s4, 26
	s_add_i32 s4, s2, s4
	s_and_b32 s5, s4, 0xffc0
	s_sub_i32 s2, s2, s5
	s_bfe_i32 s5, s2, 0x80000
	s_bfe_u32 s5, s5, 0x2000d
	s_add_i32 s5, s2, s5
	s_and_b32 s5, s5, 0xfc
	s_sub_i32 s2, s2, s5
	s_sext_i32_i8 s2, s2
	s_lshl_b32 s4, s4, 4
	s_and_b32 s4, s4, 0xfffffc00
	s_lshl_b32 s2, s2, 8
	s_add_i32 s4, s4, s2
	s_and_b32 s57, s4, 0xfffffc00
	s_bfe_u32 s98, s4, 0x20008
	v_add_u32_e32 v2, 0, v162
	s_ashr_i32 s2, s57, 31
	v_add_u32_e32 v5, 0x20000, v2
	v_or_b32_e32 v2, s57, v0
	s_waitcnt lgkmcnt(0)
	v_mov_b32_e32 v3, s2
	v_lshlrev_b64 v[2:3], 8, v[2:3]
	v_lshl_add_u64 v[2:3], s[18:19], 0, v[2:3]
	s_mov_b64 s[4:5], 0x425000f0
	v_or_b32_e32 v4, 0xfffffe00, v0
	v_lshl_add_u64 v[2:3], v[2:3], 0, s[4:5]
	s_mov_b64 s[8:9], 0
	v_mov_b32_e32 v6, 0x358637bd
	s_mov_b32 s2, 0xf800000
	v_mov_b32_e32 v7, 0x260
	s_mov_b64 s[10:11], 0x20000
	v_readfirstlane_b32 s100, v0
	s_nop 3
	s_lshr_b32 s100, s100, 8
	s_and_b32 s99, s98, 1
	s_cmp_lg_u32 s100, s99
	s_cbranch_scc1 .Ltabskip_0
	s_lshr_b32 s99, s98, 1
	s_lshl_b32 s100, s99, 17
	s_mov_b32 s101, 0
	v_lshl_add_u64 v[2:3], v[2:3], 0, s[100:101]
	s_lshl_b32 s99, s99, 11
	v_add_u32_e32 v5, s99, v5
	v_mov_b32_e32 v4, v0

.Ltabskip_0:
	s_or_b64 exec, exec, s[8:9]
	s_waitcnt lgkmcnt(0)
	s_barrier

.LBB0_812:
	s_add_u32 s94, s18, 0x3ae00000
	s_addc_u32 s95, s19, 0
	s_cmp_lt_i32 s92, 7
	s_cselect_b64 s[4:5], -1, 0
	s_cmp_gt_i32 s93, 6
	s_cselect_b64 s[6:7], -1, 0
	s_and_b64 s[8:9], s[4:5], s[6:7]
	v_readlane_b32 s42, v250, 24
	s_andn2_b64 vcc, exec, s[8:9]
	v_readlane_b32 s43, v250, 25
	s_cbranch_vccnz .LBB0_885
	s_cmpk_lt_i32 s96, 0x180
	s_cselect_b64 s[6:7], -1, 0
	s_cmpk_gt_i32 s96, 0x17f
	s_mov_b32 s2, 0
	s_cbranch_scc1 .LBB0_817
	s_ashr_i32 s2, s96, 31
	s_lshr_b32 s2, s2, 29
	s_add_i32 s2, s96, s2
	s_ashr_i32 s4, s2, 3
	s_and_b32 s2, s2, -8
	s_sub_i32 s2, s96, s2
	s_cmp_lt_i32 s2, 0
	s_cselect_b32 s5, 49, 48
	s_mul_i32 s2, s2, s5
	s_add_i32 s2, s2, s4
	s_mul_hi_i32 s4, s2, 0x2aaaaaab
	s_lshr_b32 s5, s4, 31
	s_ashr_i32 s4, s4, 3
	s_add_i32 s4, s4, s5
	s_mul_i32 s5, s4, 48
	s_sub_i32 s2, s2, s5
	s_bfe_i32 s5, s2, 0x80000
	s_bfe_u32 s5, s5, 0x2000d
	s_add_i32 s5, s2, s5
	s_and_b32 s5, s5, 0xfc
	s_sub_i32 s2, s2, s5
	s_sext_i32_i8 s2, s2
	s_lshl_b32 s4, s4, 10
	s_lshl_b32 s2, s2, 8
	s_add_i32 s4, s4, s2
	s_and_b32 s2, s4, 0xfffffc00
	s_bfe_u32 s98, s4, 0x20008
	v_add_u32_e32 v2, 0, v162
	s_ashr_i32 s4, s2, 31
	v_add_u32_e32 v5, 0x20000, v2
	v_or_b32_e32 v2, s2, v0
	v_mov_b32_e32 v3, s4
	v_lshlrev_b64 v[2:3], 8, v[2:3]
	v_lshl_add_u64 v[2:3], s[18:19], 0, v[2:3]
	s_mov_b64 s[4:5], 0x42f00030
	v_or_b32_e32 v4, 0xfffffe00, v0
	v_lshl_add_u64 v[2:3], v[2:3], 0, s[4:5]
	s_mov_b64 s[10:11], 0
	v_mov_b32_e32 v6, 0x358637bd
	s_mov_b32 s20, 0xf800000
	v_mov_b32_e32 v7, 0x260
	s_mov_b64 s[14:15], 0x20000
	v_readfirstlane_b32 s100, v0
	s_nop 3
	s_lshr_b32 s100, s100, 8
	s_and_b32 s99, s98, 1
	s_cmp_lg_u32 s100, s99
	s_cbranch_scc1 .Ltabskip_1
	s_lshr_b32 s99, s98, 1
	s_lshl_b32 s100, s99, 17
	s_mov_b32 s101, 0
	v_lshl_add_u64 v[2:3], v[2:3], 0, s[100:101]
	s_lshl_b32 s99, s99, 11
	v_add_u32_e32 v5, s99, v5
	v_mov_b32_e32 v4, v0
.LBB0_815:
	global_load_dwordx4 v[8:11], v[2:3], off offset:-48
	global_load_dwordx4 v[12:15], v[2:3], off offset:-32
	global_load_dwordx4 v[16:19], v[2:3], off offset:-16
	global_load_dwordx4 v[20:23], v[2:3], off
	v_lshl_add_u64 v[2:3], v[2:3], 0, s[14:15]
	s_waitcnt vmcnt(0)
	v_pk_add_f32 v[10:11], v[10:11], v[14:15]
	v_pk_add_f32 v[8:9], v[8:9], v[12:13]
	v_pk_add_f32 v[10:11], v[10:11], v[18:19]
	v_pk_add_f32 v[8:9], v[8:9], v[16:17]
	v_pk_add_f32 v[10:11], v[10:11], v[22:23]
	v_pk_add_f32 v[8:9], v[8:9], v[20:21]
	s_nop 0
	v_pk_mov_b32 v[12:13], v[8:9], v[10:11] op_sel:[1,0]
	v_mov_b32_e32 v9, v11
	v_pk_add_f32 v[8:9], v[12:13], v[8:9]
	s_nop 0
	v_add_f32_e32 v8, v8, v9
	v_fmamk_f32 v8, v8, 0x3a924925, v6
	v_mul_f32_e32 v9, 0x4f800000, v8
	v_cmp_gt_f32_e32 vcc, s20, v8
	s_nop 1
	v_cndmask_b32_e32 v8, v8, v9, vcc
	v_sqrt_f32_e32 v9, v8
	s_nop 0
	v_add_u32_e32 v10, -1, v9
	v_add_u32_e32 v11, 1, v9
	v_fma_f32 v12, -v10, v9, v8
	v_fma_f32 v13, -v11, v9, v8
	v_cmp_ge_f32_e64 s[4:5], 0, v12
	s_nop 1
	v_cndmask_b32_e64 v9, v9, v10, s[4:5]
	v_cmp_lt_f32_e64 s[4:5], 0, v13
	s_nop 1
	v_cndmask_b32_e64 v9, v9, v11, s[4:5]
	v_mul_f32_e32 v10, 0x37800000, v9
	v_cndmask_b32_e32 v9, v9, v10, vcc
	v_cmp_class_f32_e32 vcc, v8, v7
	s_nop 1
	v_cndmask_b32_e32 v8, v9, v8, vcc
	v_div_scale_f32 v9, s[4:5], v8, v8, 1.0
	v_rcp_f32_e32 v11, v9
	v_div_scale_f32 v10, vcc, 1.0, v8, 1.0
	v_fma_f32 v12, -v9, v11, 1.0
	v_fmac_f32_e32 v11, v12, v11
	v_mul_f32_e32 v12, v10, v11
	v_fma_f32 v13, -v9, v12, v10
	v_fmac_f32_e32 v12, v13, v11
	v_fma_f32 v9, -v9, v12, v10
	v_div_fmas_f32 v9, v9, v11, v12
	v_add_co_u32_e32 v4, vcc, 0x200, v4
	s_xor_b64 s[4:5], vcc, -1
	v_div_fixup_f32 v8, v9, v8, 1.0
	s_and_b64 s[4:5], exec, s[4:5]
	ds_write_b32 v5, v8
	s_or_b64 s[10:11], s[4:5], s[10:11]
	v_add_u32_e32 v5, 0x800, v5
	s_andn2_b64 exec, exec, s[10:11]
	s_cbranch_execnz .LBB0_815
.Ltabskip_1:
	s_or_b64 exec, exec, s[10:11]
	s_waitcnt lgkmcnt(0)
	s_barrier
.LBB0_817:
	v_lshlrev_b32_e32 v2, 4, v0
	v_and_b32_e32 v3, 32, v0
	v_bitop3_b32 v148, v2, v3, 48 bitop3:0x6c
	v_lshrrev_b32_e32 v3, 5, v0
	v_lshrrev_b32_e32 v5, 1, v0
	v_or_b32_e32 v151, 0x2000, v2
	v_bfe_u32 v150, v0, 2, 4
	v_and_b32_e32 v3, 4, v3
	v_bfe_u32 v4, v0, 2, 2
	v_and_b32_e32 v153, 24, v5
	v_lshrrev_b32_e32 v2, 7, v151
	s_movk_i32 s5, 0x70
	v_or3_b32 v3, v3, v4, v153
	v_and_or_b32 v159, v2, s5, v150
	s_movk_i32 s5, 0x60
	v_lshrrev_b32_e32 v4, 3, v0
	v_and_or_b32 v160, v2, s5, v3
	v_lshlrev_b32_e32 v2, 6, v0
	v_and_b32_e32 v149, 64, v0
	v_and_or_b32 v158, v4, 32, v3
	v_lshlrev_b32_e32 v154, 1, v153
	v_and_b32_e32 v2, 0x3c0, v2
	v_and_b32_e32 v3, 32, v162
	s_ashr_i32 s20, s96, 31
	v_readfirstlane_b32 s4, v0
	v_and_b32_e32 v152, 15, v0
	v_or_b32_e32 v156, v148, v149
	v_and_or_b32 v157, v4, 48, v150
	s_andn2_b64 vcc, exec, s[6:7]
	v_bitop3_b32 v155, v154, v3, v2 bitop3:0x36
	s_cbranch_vccnz .LBB0_837
	s_lshr_b32 s7, s20, 29
	s_add_i32 s7, s96, s7
	s_lshr_b32 s6, s4, 6
	s_ashr_i32 s10, s7, 3
	s_and_b32 s7, s7, -8
	s_lshr_b32 s5, s4, 8
	s_lshl_b32 s21, s6, 10
	s_sub_i32 s7, s96, s7
	s_cmp_lt_i32 s7, 0
	s_cselect_b32 s11, 49, 48
	s_mul_i32 s7, s7, s11
	s_add_i32 s7, s7, s10
	s_mul_hi_i32 s10, s7, 0x2aaaaaab
	s_lshr_b32 s11, s10, 31
	s_ashr_i32 s10, s10, 3
	s_add_i32 s10, s10, s11
	s_lshl_b32 s11, s10, 2
	s_mul_i32 s10, s10, 48
	s_sub_i32 s10, s7, s10
	s_bfe_i32 s7, s10, 0x80000
	s_bfe_u32 s7, s7, 0x2000d
	s_add_i32 s14, s10, s7
	s_bfe_i32 s7, s14, 0x80000
	s_and_b32 s14, s14, 0xfc
	s_sub_i32 s10, s10, s14
	v_mul_u32_u24_e32 v2, 0x380, v160
	v_lshrrev_b32_e32 v3, 1, v156
	s_sext_i32_i16 s15, s7
	s_sext_i32_i8 s10, s10
	v_or_b32_e32 v2, v2, v3
	v_mul_u32_u24_e32 v10, 0x380, v159
	s_add_i32 s71, s11, s10
	s_ashr_i32 s10, s15, 2
	v_lshlrev_b32_e32 v130, 1, v2
	v_or_b32_e32 v2, v10, v3
	s_lshr_b32 s7, s15, 2
	s_mul_hi_i32 s11, s10, 0x70000
	s_mul_i32 s10, s10, 0x70000
	v_readlane_b32 s24, v250, 17
	v_lshlrev_b32_e32 v132, 1, v2
	v_mul_u32_u24_e32 v2, 0x380, v158
	v_readlane_b32 s25, v250, 18
	s_add_u32 s54, s24, s10
	v_or_b32_e32 v2, v2, v3
	s_addc_u32 s55, s25, s11
	s_add_i32 s26, s21, 0
	v_lshlrev_b32_e32 v134, 1, v2
	s_add_i32 m0, s26, 0x10000
	s_mul_i32 s22, s71, 0x70000
	global_load_lds_dwordx4 v134, s[54:55]
	s_add_i32 m0, s26, 0x12000
	s_add_u32 s10, s54, 0x38000
	global_load_lds_dwordx4 v130, s[54:55]
	s_addc_u32 s11, s55, 0
	s_add_i32 m0, s26, 0x14000
	v_mul_u32_u24_e32 v11, 0x380, v157
	global_load_lds_dwordx4 v134, s[10:11]
	s_add_i32 m0, s26, 0x16000
	s_mul_hi_i32 s14, s71, 0x70000
	s_add_u32 s30, s64, s22
	v_or_b32_e32 v2, v3, v11
	s_addc_u32 s31, s65, s14
	s_add_i32 s27, s26, 0x2000
	v_lshlrev_b32_e32 v136, 1, v2
	global_load_lds_dwordx4 v130, s[10:11]
	s_mov_b32 m0, s26
	s_add_u32 s10, s30, 0x38000
	global_load_lds_dwordx4 v136, s[30:31]
	s_mov_b32 m0, s27
	s_addc_u32 s11, s31, 0
	s_add_i32 s36, s26, 0x4000
	global_load_lds_dwordx4 v132, s[30:31]
	s_mov_b32 m0, s36
	s_add_i32 s37, s26, 0x6000
	global_load_lds_dwordx4 v136, s[10:11]
	s_mov_b32 m0, s37
	v_mov_b32_e32 v135, 0
	global_load_lds_dwordx4 v132, s[10:11]
	v_mov_b32_e32 v131, v135
	v_mov_b32_e32 v137, v135
	v_mov_b32_e32 v133, v135
	s_cmp_eq_u32 s5, 1
	s_mov_b32 s38, 0
	v_lshl_add_u64 v[8:9], s[54:55], 0, v[134:135]
	v_lshl_add_u64 v[6:7], s[54:55], 0, v[130:131]
	v_lshl_add_u64 v[2:3], s[30:31], 0, v[136:137]
	s_cselect_b64 s[10:11], -1, 0
	s_cmp_lg_u32 s5, 1
	v_lshl_add_u64 v[4:5], s[30:31], 0, v[132:133]
	s_cbranch_scc1 .LBB0_820
	s_barrier

.LBB0_858:
	s_ashr_i32 s2, s2, 3
	s_add_i32 s2, s11, s2
	s_ashr_i32 s4, s2, 31
	s_lshr_b32 s4, s4, 26
	s_add_i32 s4, s2, s4
	s_and_b32 s5, s4, 0xffc0
	s_sub_i32 s2, s2, s5
	s_bfe_i32 s5, s2, 0x80000
	s_bfe_u32 s5, s5, 0x2000d
	s_add_i32 s5, s2, s5
	s_and_b32 s5, s5, 0xfc
	s_sub_i32 s2, s2, s5
	s_sext_i32_i8 s2, s2
	s_lshl_b32 s4, s4, 4
	s_and_b32 s4, s4, 0xfffffc00
	s_lshl_b32 s2, s2, 8
	s_add_i32 s4, s4, s2
	s_and_b32 s21, s4, 0xfffffc00
	s_bfe_u32 s98, s4, 0x20008
	v_add_u32_e32 v2, 0, v162
	s_ashr_i32 s2, s21, 31
	v_add_u32_e32 v5, 0x21000, v2
	v_or_b32_e32 v2, s21, v0
	v_mov_b32_e32 v3, s2
	v_lshlrev_b64 v[2:3], 8, v[2:3]
	v_lshl_add_u64 v[2:3], s[18:19], 0, v[2:3]
	s_mov_b64 s[4:5], 0x43100010
	v_or_b32_e32 v4, 0xfffffe00, v0
	v_lshl_add_u64 v[2:3], v[2:3], 0, s[4:5]
	s_mov_b64 s[10:11], 0
	v_mov_b32_e32 v6, 0x358637bd
	s_mov_b32 s2, 0xf800000
	v_mov_b32_e32 v7, 0x260
	s_mov_b64 s[14:15], 0x20000
	v_readfirstlane_b32 s100, v0
	s_nop 3
	s_lshr_b32 s100, s100, 8
	s_and_b32 s99, s98, 1
	s_cmp_lg_u32 s100, s99
	s_cbranch_scc1 .Ltabskip_2
	s_lshr_b32 s99, s98, 1
	s_lshl_b32 s100, s99, 17
	s_mov_b32 s101, 0
	v_lshl_add_u64 v[2:3], v[2:3], 0, s[100:101]
	s_lshl_b32 s99, s99, 11
	v_add_u32_e32 v5, s99, v5
	v_mov_b32_e32 v4, v0
.LBB0_859:
	global_load_dwordx4 v[8:11], v[2:3], off offset:-16
	global_load_dwordx4 v[12:15], v[2:3], off
	v_lshl_add_u64 v[2:3], v[2:3], 0, s[14:15]
	s_waitcnt vmcnt(0)
	v_pk_add_f32 v[10:11], v[10:11], v[14:15]
	v_pk_add_f32 v[8:9], v[8:9], v[12:13]
	s_nop 0
	v_pk_mov_b32 v[12:13], v[8:9], v[10:11] op_sel:[1,0]
	v_mov_b32_e32 v9, v11
	v_pk_add_f32 v[8:9], v[12:13], v[8:9]
	s_nop 0
	v_add_f32_e32 v8, v8, v9
	v_fmamk_f32 v8, v8, 0x3b000000, v6
	v_mul_f32_e32 v9, 0x4f800000, v8
	v_cmp_gt_f32_e32 vcc, s2, v8
	s_nop 1
	v_cndmask_b32_e32 v8, v8, v9, vcc
	v_sqrt_f32_e32 v9, v8
	s_nop 0
	v_add_u32_e32 v10, -1, v9
	v_add_u32_e32 v11, 1, v9
	v_fma_f32 v12, -v10, v9, v8
	v_fma_f32 v13, -v11, v9, v8
	v_cmp_ge_f32_e64 s[4:5], 0, v12
	s_nop 1
	v_cndmask_b32_e64 v9, v9, v10, s[4:5]
	v_cmp_lt_f32_e64 s[4:5], 0, v13
	s_nop 1
	v_cndmask_b32_e64 v9, v9, v11, s[4:5]
	v_mul_f32_e32 v10, 0x37800000, v9
	v_cndmask_b32_e32 v9, v9, v10, vcc
	v_cmp_class_f32_e32 vcc, v8, v7
	s_nop 1
	v_cndmask_b32_e32 v8, v9, v8, vcc
	v_div_scale_f32 v9, s[4:5], v8, v8, 1.0
	v_rcp_f32_e32 v11, v9
	v_div_scale_f32 v10, vcc, 1.0, v8, 1.0
	v_fma_f32 v12, -v9, v11, 1.0
	v_fmac_f32_e32 v11, v12, v11
	v_mul_f32_e32 v12, v10, v11
	v_fma_f32 v13, -v9, v12, v10
	v_fmac_f32_e32 v12, v13, v11
	v_fma_f32 v9, -v9, v12, v10
	v_div_fmas_f32 v9, v9, v11, v12
	v_add_co_u32_e32 v4, vcc, 0x200, v4
	s_xor_b64 s[4:5], vcc, -1
	v_div_fixup_f32 v8, v9, v8, 1.0
	s_and_b64 s[4:5], exec, s[4:5]
	ds_write_b32 v5, v8
	s_or_b64 s[10:11], s[4:5], s[10:11]
	v_add_u32_e32 v5, 0x800, v5
	s_andn2_b64 exec, exec, s[10:11]
	s_cbranch_execnz .LBB0_859
.Ltabskip_2:
	s_or_b64 exec, exec, s[10:11]
	s_waitcnt lgkmcnt(0)
	s_barrier
.LBB0_861:
	s_andn2_b64 vcc, exec, s[6:7]
	v_readfirstlane_b32 s14, v0
	s_cbranch_vccnz .LBB0_885
	s_lshr_b32 s2, s20, 29
	s_add_i32 s2, s96, s2
	s_and_b32 s4, s2, -8
	s_sub_i32 s7, s96, s4
	s_cmp_gt_i32 s7, -1
	s_cbranch_scc0 .LBB0_864
	s_lshl_b32 s6, s7, 6
	s_cbranch_execz .LBB0_865
	s_branch .LBB0_866

.LBB0_1357:
	s_ashr_i32 s2, s2, 3
	s_add_i32 s2, s9, s2
	s_ashr_i32 s4, s2, 31
	s_lshr_b32 s4, s4, 26
	s_add_i32 s4, s2, s4
	s_and_b32 s5, s4, 0xffc0
	s_sub_i32 s2, s2, s5
	s_bfe_i32 s5, s2, 0x80000
	s_bfe_u32 s5, s5, 0x2000d
	s_add_i32 s5, s2, s5
	s_and_b32 s5, s5, 0xfc
	s_sub_i32 s2, s2, s5
	s_sext_i32_i8 s2, s2
	s_lshl_b32 s4, s4, 4
	s_and_b32 s4, s4, 0xfffffc00
	s_lshl_b32 s2, s2, 8
	s_add_i32 s4, s4, s2
	s_and_b32 s2, s4, 0xfffffc00
	s_bfe_u32 s98, s4, 0x20008
	v_or_b32_e32 v2, s2, v0
	v_ashrrev_i32_e32 v3, 31, v2
	s_waitcnt vmcnt(0)
	v_add_u32_e32 v8, 0, v162
	v_lshlrev_b64 v[2:3], 8, v[2:3]
	v_or_b32_e32 v6, 0xfffffe00, v0
	v_add_u32_e32 v7, 0x20000, v8
	v_lshl_add_u64 v[2:3], s[18:19], 0, v[2:3]
	s_mov_b64 s[4:5], 0x42b00030
	v_lshl_add_u64 v[4:5], v[2:3], 0, s[4:5]
	s_mov_b64 s[24:25], 0
	v_mov_b32_e32 v9, 0x358637bd
	s_mov_b32 s8, 0xf800000
	v_mov_b32_e32 v10, 0x260
	s_mov_b64 s[30:31], 0x20000
	v_mov_b32_e32 v11, v7
	v_mov_b32_e32 v12, v6
	v_readfirstlane_b32 s100, v0
	s_nop 3
	s_lshr_b32 s100, s100, 8
	s_and_b32 s99, s98, 1
	s_cmp_lg_u32 s100, s99
	s_cbranch_scc1 .Ltabskip_3
	s_lshr_b32 s99, s98, 1
	s_lshl_b32 s100, s99, 17
	s_mov_b32 s101, 0
	v_lshl_add_u64 v[4:5], v[4:5], 0, s[100:101]
	s_lshl_b32 s99, s99, 11
	v_add_u32_e32 v11, s99, v11
	v_mov_b32_e32 v12, v0

.Ltabskip_3:
	s_or_b64 exec, exec, s[24:25]
	s_mov_b64 s[4:5], 0x42b000b0
	v_add_u32_e32 v4, 0x21000, v8
	v_lshl_add_u64 v[2:3], v[2:3], 0, s[4:5]
	s_mov_b64 s[24:25], 0
	v_mov_b32_e32 v5, 0x358637bd
	s_mov_b32 s8, 0xf800000
	v_mov_b32_e32 v8, 0x260
	s_mov_b64 s[30:31], 0x20000
	v_mov_b32_e32 v9, v6
	s_waitcnt lgkmcnt(0)
	s_barrier
	v_readfirstlane_b32 s100, v0
	s_nop 3
	s_lshr_b32 s100, s100, 8
	s_and_b32 s99, s98, 1
	s_cmp_lg_u32 s100, s99
	s_cbranch_scc1 .Ltabskip_4
	s_lshr_b32 s99, s98, 1
	s_lshl_b32 s100, s99, 17
	s_mov_b32 s101, 0
	v_lshl_add_u64 v[2:3], v[2:3], 0, s[100:101]
	s_lshl_b32 s99, s99, 11
	v_add_u32_e32 v4, s99, v4
	v_mov_b32_e32 v9, v0

.Ltabskip_4:
	s_or_b64 exec, exec, s[24:25]
	s_mov_b64 s[4:5], 0
	s_waitcnt lgkmcnt(0)
	s_barrier

.LBB0_2157:
	s_cmp_lt_i32 s92, 18
	s_cselect_b64 s[4:5], -1, 0
	s_cmp_gt_i32 s93, 17
	s_cselect_b64 s[6:7], -1, 0
	s_and_b64 s[6:7], s[4:5], s[6:7]
	s_andn2_b64 vcc, exec, s[6:7]
	s_cbranch_vccnz .LBB0_2324
	s_cmpk_lt_i32 s96, 0xac0
	s_cselect_b64 s[8:9], -1, 0
	s_cmpk_gt_i32 s96, 0xabf
	s_mov_b32 s2, 0
	s_cbranch_scc1 .LBB0_2162
	s_ashr_i32 s2, s96, 31
	s_lshr_b32 s2, s2, 29
	s_add_i32 s2, s96, s2
	s_ashr_i32 s4, s2, 3
	s_and_b32 s2, s2, -8
	s_sub_i32 s2, s96, s2
	s_cmp_lt_i32 s2, 0
	s_movk_i32 s5, 0x159
	s_cselect_b32 s5, s5, 0x158
	s_mul_i32 s2, s2, s5
	s_add_i32 s2, s2, s4
	s_mul_hi_i32 s4, s2, 0x2fa0be83
	s_lshr_b32 s5, s4, 31
	s_ashr_i32 s4, s4, 6
	s_add_i32 s4, s4, s5
	s_mul_i32 s5, s4, 0x158
	s_sub_i32 s2, s2, s5
	s_bfe_u32 s5, s2, 0x2001d
	s_add_i32 s5, s2, s5
	s_and_b32 s5, s5, 0xfffc
	s_sub_i32 s2, s2, s5
	s_sext_i32_i16 s2, s2
	s_lshl_b32 s4, s4, 10
	s_lshl_b32 s2, s2, 8
	s_add_i32 s4, s4, s2
	s_and_b32 s2, s4, 0xfffffc00
	s_bfe_u32 s98, s4, 0x20008
	v_add_u32_e32 v2, 0, v162
	s_ashr_i32 s4, s2, 31
	v_add_u32_e32 v5, 0x20000, v2
	v_or_b32_e32 v2, s2, v0
	v_mov_b32_e32 v3, s4
	v_lshlrev_b64 v[2:3], 8, v[2:3]
	v_lshl_add_u64 v[2:3], s[18:19], 0, v[2:3]
	s_mov_b64 s[4:5], 0x429000f0
	v_or_b32_e32 v4, 0xfffffe00, v0
	v_lshl_add_u64 v[2:3], v[2:3], 0, s[4:5]
	s_mov_b64 s[22:23], 0
	s_waitcnt vmcnt(0)
	v_mov_b32_e32 v6, 0x358637bd
	s_mov_b32 s14, 0xf800000
	v_mov_b32_e32 v7, 0x260
	s_mov_b64 s[24:25], 0x20000
	v_readfirstlane_b32 s100, v0
	s_nop 3
	s_lshr_b32 s100, s100, 8
	s_and_b32 s99, s98, 1
	s_cmp_lg_u32 s100, s99
	s_cbranch_scc1 .Ltabskip_5
	s_lshr_b32 s99, s98, 1
	s_lshl_b32 s100, s99, 17
	s_mov_b32 s101, 0
	v_lshl_add_u64 v[2:3], v[2:3], 0, s[100:101]
	s_lshl_b32 s99, s99, 11
	v_add_u32_e32 v5, s99, v5
	v_mov_b32_e32 v4, v0

.Ltabskip_5:
	s_or_b64 exec, exec, s[22:23]
	s_waitcnt lgkmcnt(0)
	s_barrier
